# sp7 late: piece workgroups complete the deferred barrier-7 wait at the top of the piece's 4th (last) K iteration instead of the 3rd (async poll issued at the 3rd)
# baseline (speedup 1.0000x reference)
; __device__ __forceinline__ unsigned xb_ld(unsigned* p)              { return __hip_atomic_load(p, __ATOMIC_RELAXED, __HIP_MEMORY_SCOPE_AGENT); }
; __device__ __forceinline__ unsigned xb_add(unsigned* p, unsigned v) { return __hip_atomic_fetch_add(p, v, __ATOMIC_RELAXED, __HIP_MEMORY_SCOPE_AGENT); }
; #define XB_SPIN(cond, bar) do { unsigned _sp = 0; while (cond) { __builtin_amdgcn_s_sleep(1); \
;     if ((++_sp & 255u) == 0u) { if (xb_ld(&(bar)[XB_TMO])) break; if (_sp > XB_SPIN_CAP) { atomicAdd(&(bar)[XB_TMO], 1u); break; } } } } while (0)
;     __host__ __device__ void init(int M, int N, int K, int G_, int c_, int tailM_, int nsplit_) { so.init(M, N, K, G_, c_); tailM = tailM_; nsplit = nsplit_; npieces = tailM_ * so.nN * nsplit_; }
; __device__ __forceinline__ void xcd_barrier(const XcdBarrier& b) {
;     ...
;             else XB_SPIN(xb_ld(&bar[XB_TOPGEN]) == tg, bar);
;             __builtin_amdgcn_fence(__ATOMIC_ACQUIRE, "agent");
;             xb_add(&bar[XB_XGEN(b.x)], 1u);
;             asm volatile("s_waitcnt vmcnt(0)" ::: "memory");
;         } else {
;             XB_SPIN(xb_ld(&bar[XB_XGEN(b.x)]) == gen, bar);
;             __builtin_amdgcn_fence(__ATOMIC_ACQUIRE, "agent");
;             asm volatile("s_waitcnt vmcnt(0)" ::: "memory");
; __global__ void __launch_bounds__(512, 2) fwd_megakernel(Params P) {
;     ...
;     xcd_barrier(bar);
;     {
;         pg8::Gemm g{(const bf16_t*)(ws + WS_U), (const bf16_t*)(ws + WS_WDN), MT, DM, FF}; pg8::TailSplitOrder S; S.init(MP, DM, FF, G, bx, MS / 256, NSPLIT_DN);
;         pg8::EpiDownNorm E{(const bf16_t*)(ws + WS_H1B), P.out + O_Y, (bf16_t*)(ws + WS_SLAB), P.norm_f, (float*)(ws + WS_XBUF), (unsigned*)(ws + WS_CNT)};
;         pg8::gemm_phase<pg8::EpiDownNorm, pg8::TailSplitOrder, true, true>(lds, g, S, E, wave0);
.Lsp7_h:
	s_cmp_eq_u32 s101, 0x8888
	s_cbranch_scc1 .Lnb8_h
	s_cmp_eq_u32 s101, 0x9999
	s_cbranch_scc1 .Lnb8_c
	s_cmp_eq_u32 s73, 6
	s_cbranch_scc0 .Lsp7_h2
	s_mov_b64 exec, 1
	s_lshl_b32 s98, s33, 8
	s_add_u32 s98, s98, 0x82400
	v_mov_b32_e32 v246, s98
	global_load_dword v247, v246, s[68:69] sc1
	s_mov_b64 exec, -1
	s_branch .Lsp7_back
.Lsp7_h2:
	s_cmp_eq_u32 s73, 8
	s_cbranch_scc0 .Lsp7_back
	s_mov_b64 exec, 1
	v_mov_b32_e32 v248, s101
	s_mov_b32 s98, 0x40000
